# Mixer phase: waves 4-7 run attention first then short-conv (waves 0-3 conv then attention) so memory-bound conv overlaps VALU-bound attention on each SIMD
# speedup vs baseline: 1.1000x; 1.1000x over previous
_Z10fwd_kernel6Params:
	s_mov_b64 s[70:71], s[0:1]
	s_load_dwordx2 s[0:1], s[0:1], 0x68
	s_nop 0
	s_load_dwordx4 s[56:59], s[70:71], 0x70
	v_and_b32_e32 v1, 0x3ff, v0
	s_mov_b32 s8, 0
	s_mov_b32 s100, 0
	v_readfirstlane_b32 s3, v1
	v_cmp_eq_u32_e64 s[4:5], 0, v1
	s_and_saveexec_b64 s[6:7], s[4:5]
	s_cbranch_execz .LBB0_2
	s_add_i32 s9, 0, 0x20800
	v_mov_b32_e32 v2, 0
	v_mov_b32_e32 v3, s9
	s_add_i32 s9, 0, 0x20804
	ds_write_b32 v3, v2
	v_mov_b32_e32 v3, s9
	s_add_i32 s9, 0, 0x20808
	ds_write_b32 v3, v2
	v_mov_b32_e32 v3, s9
	s_add_i32 s9, 0, 0x2080c
	ds_write_b32 v3, v2
	v_mov_b32_e32 v3, s9
	ds_write_b32 v3, v2

.LBB0_11:
	s_cmp_ge_u32 s74, 4
	s_cselect_b32 s100, 1, 4
	s_mov_b32 s0, s74
	s_mov_b32 s62, s44
	v_lshl_add_u32 v248, s0, 6, v213
	s_mov_b64 s[0:1], s[70:71]
	s_load_dwordx2 s[8:9], s[0:1], 0x68
	s_mov_b64 s[20:21], -1
	s_mov_b64 s[16:17], 0
	s_mov_b64 s[18:19], 0
	s_waitcnt lgkmcnt(0)
	s_add_u32 s12, s8, 0x3100000
	s_addc_u32 s13, s9, 0
	s_add_u32 s14, s8, 0x17100000
	s_addc_u32 s15, s9, 0
	s_cmp_lt_i32 s56, 11
	s_cbranch_scc1 .LBB0_25
	s_cmp_eq_u32 s56, 11
	s_mov_b64 s[18:19], -1
	s_cbranch_scc0 .LBB0_17
	v_ashrrev_i32_e32 v0, 4, v248
	v_and_b32_e32 v0, -4, v0
	v_readlane_b32 s4, v254, 2
	s_waitcnt vmcnt(0)
	s_nop 0
	v_add_u32_e32 v22, s4, v0
	v_cmp_gt_i32_e32 vcc, s64, v22
	s_and_saveexec_b64 s[18:19], vcc
	s_cbranch_execz .LBB0_16
	s_load_dwordx4 s[20:23], s[0:1], 0x58
	v_lshlrev_b32_e32 v0, 3, v248
	v_and_b32_e32 v18, 0x1f8, v0
	v_lshlrev_b32_e32 v0, 2, v18
	v_lshlrev_b32_e32 v18, 1, v18
	s_waitcnt lgkmcnt(0)
	global_load_dwordx4 v[2:5], v0, s[20:21] offset:16
	global_load_dwordx4 v[6:9], v0, s[20:21]
	global_load_dwordx4 v[10:13], v0, s[20:21] offset:2064
	global_load_dwordx4 v[14:17], v0, s[20:21] offset:2048
	s_load_dword s4, s[88:89], 0x0
	v_mov_b32_e32 v19, v1
	v_lshl_add_u64 v[24:25], s[12:13], 0, v[18:19]
	v_lshl_add_u64 v[26:27], s[22:23], 0, v[0:1]
	s_mov_b64 s[20:21], 0
	s_waitcnt lgkmcnt(0)
	s_lshl_b32 s22, s4, 5

.Lmx_setup:
	s_load_dword s38, s[88:89], 0x0
	v_readfirstlane_b32 s17, v248
	s_mov_b32 s22, s75
	s_mov_b32 s19, s2
	s_waitcnt lgkmcnt(0)
	s_and_b32 s4, s38, 7
	s_cmp_lg_u32 s4, 0
	s_cbranch_scc1 .LBB0_23
	s_ashr_i32 s4, s38, 3
	v_readlane_b32 s5, v254, 49
	s_mul_i32 s4, s4, s5
	v_readlane_b32 s5, v254, 50
	s_add_i32 s19, s4, s5
	s_lshl_b32 s22, s19, 3

.LBB0_111:
	s_add_u32 s22, s8, 0x13100000
	s_addc_u32 s23, s9, 0
	v_writelane_b32 v255, s30, 15
	s_cmp_eq_u32 s100, 1
	s_cbranch_scc0 .Lmx_conv
	s_mov_b32 s100, 2
	s_waitcnt vmcnt(0)
	s_branch .LBB0_114
.Lmx_conv:
	s_cmp_lt_i32 s25, 1
	s_cbranch_scc1 .LBB0_114
	s_add_i32 s39, s24, s25
	s_add_u32 s30, s8, 0x13100400
	s_addc_u32 s31, s9, 0
	s_add_i32 s4, s24, 1
	v_and_b32_e32 v36, 64, v213
	s_ashr_i32 s5, s4, 31
	v_xor_b32_e32 v0, 1, v213
	v_add_u32_e32 v36, 64, v36
	s_lshl_b64 s[6:7], s[4:5], 11
	v_cmp_lt_i32_e32 vcc, v0, v36
	s_add_u32 s26, s30, s6
	s_addc_u32 s27, s31, s7
	v_cndmask_b32_e32 v0, v213, v0, vcc
	s_add_i32 s5, s34, 0x1800
	v_lshlrev_b32_e32 v106, 2, v0
	v_xor_b32_e32 v0, 2, v213
	s_mul_hi_i32 s4, s4, 0x1800
	s_add_u32 s28, s8, s5
	v_cmp_lt_i32_e32 vcc, v0, v36
	s_addc_u32 s29, s9, s4
	s_ashr_i32 s25, s24, 31
	v_cndmask_b32_e32 v0, v213, v0, vcc
	s_lshl_b64 s[4:5], s[24:25], 11
	v_lshlrev_b32_e32 v107, 2, v0
	v_xor_b32_e32 v0, 4, v213
	s_add_u32 s30, s30, s4
	v_cmp_lt_i32_e32 vcc, v0, v36
	s_addc_u32 s31, s31, s5
	v_mov_b32_e32 v35, v1
	v_cndmask_b32_e32 v0, v213, v0, vcc
	s_mul_hi_i32 s4, s24, 0x1800
	s_add_u32 s34, s8, s34
	v_lshl_add_u64 v[82:83], s[20:21], 0, v[34:35]
	v_lshlrev_b32_e32 v108, 2, v0
	v_lshl_add_u64 v[84:85], s[22:23], 0, v[34:35]
	v_lshlrev_b32_e32 v0, 4, v112
	s_addc_u32 s35, s9, s4

.LBB0_114:
	s_cmp_eq_u32 s100, 3
	s_cbranch_scc1 .LBB0_370
	s_cmpk_eq_i32 s38, 0x100
	s_cbranch_scc0 .LBB0_370
	s_ashr_i32 s4, s19, 31
	s_lshr_b32 s4, s4, 27
	s_add_i32 s4, s19, s4
	s_ashr_i32 s5, s4, 5
	s_and_b32 s4, s4, 0x1fffffe0
	s_sub_i32 s4, s19, s4
	s_lshl_b32 s4, s4, 3
	s_add_i32 s4, s4, s18
	s_ashr_i32 s6, s4, 31
	s_lshr_b32 s6, s6, 26
	s_add_i32 s6, s4, s6
	s_lshl_b64 s[24:25], s[16:17], 9
	s_lshl_b32 s5, s5, 4
	s_ashr_i32 s17, s6, 6
	s_add_i32 s17, s17, s5
	s_and_b32 s5, s6, 0xffffffc0
	s_sub_i32 s97, s4, s5
	s_lshl_b32 s4, s97, 5
	s_and_b32 s36, s4, 0xffffff80
	s_and_b32 s4, s97, 3
	s_or_b32 s34, s36, s4
	s_ashr_i32 s4, s17, 3
	v_lshlrev_b32_e32 v0, 2, v248
	s_mul_hi_i32 s5, s4, 0xc00000
	s_mul_i32 s4, s4, 0xc00000
	v_and_b32_e32 v0, 0x7c, v0
	s_add_u32 s26, s20, s4
	v_or_b32_e32 v0, s34, v0
	s_movk_i32 s4, 0xc00
	s_waitcnt vmcnt(7)
	v_mul_lo_u32 v2, v0, s4
	s_addc_u32 s27, s21, s5
	v_ashrrev_i32_e32 v3, 31, v2
	s_and_b32 s4, s6, 0x1c0
	v_lshl_add_u64 v[2:3], v[2:3], 1, s[26:27]
	s_lshl_b32 s84, s4, 1
	v_lshrrev_b32_e32 v0, 1, v248
	v_lshl_add_u64 v[2:3], v[2:3], 0, s[84:85]
	v_and_b32_e32 v0, 16, v0
	v_lshl_add_u64 v[2:3], v[2:3], 0, v[0:1]
	global_load_dwordx4 v[64:67], v[2:3], off
	global_load_dwordx4 v[68:71], v[2:3], off offset:32
	global_load_dwordx4 v[72:75], v[2:3], off offset:64
	global_load_dwordx4 v[76:79], v[2:3], off offset:96
	s_load_dwordx2 s[28:29], s[0:1], 0x20
	s_mov_b32 s19, 0
	s_mov_b64 s[30:31], -1
	s_cmpk_gt_i32 s34, 0x60
	s_mov_b32 s35, 0
	s_cbranch_scc1 .LBB0_125
	s_cmp_gt_i32 s34, 64
	s_cbranch_scc1 .LBB0_121
	s_cmp_gt_i32 s34, 32
	s_cbranch_scc1 .LBB0_122
	s_cmp_gt_i32 s34, 0
	s_cbranch_scc1 .LBB0_123
	s_cmpk_gt_i32 s34, 0xffe0
	s_cbranch_scc1 .LBB0_124
	s_cmpk_gt_i32 s36, 0x203
	s_cselect_b32 s6, 11, 23
	s_cmp_gt_u32 s34, 0xffffff80
	s_cselect_b64 s[30:31], -1, 0
	s_and_b64 s[4:5], s[30:31], exec
	s_cselect_b32 s35, 7, s6
	s_branch .LBB0_125

.LBB0_370:
	v_readlane_b32 s70, v255, 6
	v_readlane_b32 s72, v255, 8
	v_readlane_b32 s88, v255, 11
	s_mov_b64 s[20:21], 0
	v_readlane_b32 s71, v255, 7
	v_readlane_b32 s73, v255, 9
	v_readlane_b32 s74, v255, 10
	v_readlane_b32 s89, v255, 12
	v_readlane_b32 s75, v255, 13
	s_movk_i32 s76, 0xc1
	s_mov_b32 s77, 0x20000
	s_mov_b32 s78, 0x40000
	s_mov_b32 s79, 0x60000
	s_mov_b32 s94, 0x80000
	s_mov_b32 s95, 0xa0000
	s_mov_b32 s96, 0xc0000
	s_mov_b32 s97, 0xe0000
	s_mov_b32 s48, 0x100000
	s_mov_b32 s49, 0x120000
	s_mov_b64 s[50:51], 0x5800
	v_readlane_b32 s30, v255, 15
	s_mov_b64 s[4:5], 0
	s_cmp_eq_u32 s100, 2
	s_cbranch_scc0 .Lmx_end
	s_mov_b32 s100, 3
	s_waitcnt vmcnt(0) lgkmcnt(0)
	s_mov_b64 s[0:1], s[70:71]
	s_branch .Lmx_setup
.Lmx_end:
.LBB0_371:
.LBB0_372:
	s_andn2_b64 vcc, exec, s[20:21]
	s_mov_b32 s44, s62
	s_cbranch_vccnz .LBB0_41

	.amdhsa_kernel _Z10fwd_kernel6Params
		.amdhsa_group_segment_fixed_size 0
		.amdhsa_private_segment_fixed_size 0
		.amdhsa_kernarg_size 384
		.amdhsa_user_sgpr_count 2
		.amdhsa_user_sgpr_dispatch_ptr 0
		.amdhsa_user_sgpr_queue_ptr 0
		.amdhsa_user_sgpr_kernarg_segment_ptr 1
		.amdhsa_user_sgpr_dispatch_id 0
		.amdhsa_user_sgpr_kernarg_preload_length 0
		.amdhsa_user_sgpr_kernarg_preload_offset 0
		.amdhsa_user_sgpr_private_segment_size 0
		.amdhsa_uses_dynamic_stack 0
		.amdhsa_enable_private_segment 0
		.amdhsa_system_sgpr_workgroup_id_x 1
		.amdhsa_system_sgpr_workgroup_id_y 0
		.amdhsa_system_sgpr_workgroup_id_z 0
		.amdhsa_system_sgpr_workgroup_info 0
		.amdhsa_system_vgpr_workitem_id 2
		.amdhsa_next_free_vgpr 256
		.amdhsa_next_free_sgpr 102
		.amdhsa_accum_offset 256
		.amdhsa_reserve_vcc 1
		.amdhsa_float_round_mode_32 0
		.amdhsa_float_round_mode_16_64 0
		.amdhsa_float_denorm_mode_32 3
		.amdhsa_float_denorm_mode_16_64 3
		.amdhsa_dx10_clamp 1
		.amdhsa_ieee_mode 1
		.amdhsa_fp16_overflow 0
		.amdhsa_tg_split 0
		.amdhsa_exception_fp_ieee_invalid_op 0
		.amdhsa_exception_fp_denorm_src 0
		.amdhsa_exception_fp_ieee_div_zero 0
		.amdhsa_exception_fp_ieee_overflow 0
		.amdhsa_exception_fp_ieee_underflow 0
		.amdhsa_exception_fp_ieee_inexact 0
		.amdhsa_exception_int_div_zero 0
	.end_amdhsa_kernel

amdhsa.kernels:
  - .agpr_count:     0
    .args:
      - .offset:         0
        .size:           128
        .value_kind:     by_value
      - .offset:         128
        .size:           4
        .value_kind:     hidden_block_count_x
      - .offset:         132
        .size:           4
        .value_kind:     hidden_block_count_y
      - .offset:         136
        .size:           4
        .value_kind:     hidden_block_count_z
      - .offset:         140
        .size:           2
        .value_kind:     hidden_group_size_x
      - .offset:         142
        .size:           2
        .value_kind:     hidden_group_size_y
      - .offset:         144
        .size:           2
        .value_kind:     hidden_group_size_z
      - .offset:         146
        .size:           2
        .value_kind:     hidden_remainder_x
      - .offset:         148
        .size:           2
        .value_kind:     hidden_remainder_y
      - .offset:         150
        .size:           2
        .value_kind:     hidden_remainder_z
      - .offset:         168
        .size:           8
        .value_kind:     hidden_global_offset_x
      - .offset:         176
        .size:           8
        .value_kind:     hidden_global_offset_y
      - .offset:         184
        .size:           8
        .value_kind:     hidden_global_offset_z
      - .offset:         192
        .size:           2
        .value_kind:     hidden_grid_dims
      - .offset:         216
        .size:           8
        .value_kind:     hidden_multigrid_sync_arg
      - .offset:         248
        .size:           4
        .value_kind:     hidden_dynamic_lds_size
    .group_segment_fixed_size: 0
    .kernarg_segment_align: 8
    .kernarg_segment_size: 384
    .language:       OpenCL C
    .language_version:
      - 2
      - 0
    .max_flat_workgroup_size: 512
    .name:           _Z10fwd_kernel6Params
    .private_segment_fixed_size: 0
    .sgpr_count:     108
    .sgpr_spill_count: 87
    .symbol:         _Z10fwd_kernel6Params.kd
    .uniform_work_group_size: 1
    .uses_dynamic_stack: false
    .vgpr_count:     256
    .vgpr_spill_count: 0
    .wavefront_size: 64
